# v41 + softmax attention: running max folded into QK MFMA accumulator init (C = -m), removing 32 v_sub per key tile
# speedup vs baseline: 1.0057x; 1.0057x over previous
.LBB0_913:
	s_xor_b64 s[0:1], s[2:3], -1
	v_writelane_b32 v244, s0, 9
	v_mov_b32_e32 v2, v0
	v_readlane_b32 s6, v245, 14
	v_writelane_b32 v244, s1, 10
	s_and_b64 s[0:1], s[2:3], exec
	v_readlane_b32 s0, v244, 3
	v_readlane_b32 s1, v244, 4
	s_cselect_b32 s0, s1, s0
	v_readlane_b32 s2, v244, 5
	s_lshl_b32 s9, s0, 8
	s_lshl_b32 s1, s0, 2
	s_lshl_b32 s2, s2, 1
	s_lshl_b32 s0, s0, 16
	s_or_b32 s2, s0, s2
	v_mov_b32_e32 v12, v0
	v_readlane_b32 s7, v245, 15
	s_add_u32 s6, s6, s2
	s_addc_u32 s7, s7, 0
	v_readfirstlane_b32 s2, v12
	s_ashr_i32 s3, s2, 6
	s_and_b32 s2, s2, 0x3fffffc0
	s_lshl_b32 s2, s2, 2
	v_and_b32_e32 v13, 31, v12
	s_add_i32 s95, s2, 0
	s_lshl_b32 s2, s3, 5
	v_or_b32_e32 v4, s2, v13
	v_ashrrev_i32_e32 v5, 31, v4
	v_bfe_u32 v14, v12, 5, 1
	v_lshlrev_b64 v[4:5], 8, v[4:5]
	v_lshl_add_u64 v[4:5], s[6:7], 0, v[4:5]
	v_lshlrev_b32_e32 v2, 4, v14
	v_lshl_add_u64 v[4:5], v[4:5], 0, v[2:3]
	global_load_dwordx4 v[100:103], v[4:5], off offset:128
	global_load_dwordx4 v[104:107], v[4:5], off offset:160
	global_load_dwordx4 v[108:111], v[4:5], off offset:192
	global_load_dwordx4 v[112:115], v[4:5], off offset:224
	v_ashrrev_i32_e32 v5, 4, v12
	v_lshlrev_b32_e32 v6, 1, v5
	v_lshrrev_b32_e32 v7, 1, v5
	v_and_b32_e32 v4, 0x1fffff3, v5
	v_and_b32_e32 v6, 8, v6
	v_and_b32_e32 v7, 4, v7
	v_or3_b32 v4, v4, v6, v7
	v_and_b32_e32 v6, 15, v12
	v_bitop3_b32 v6, v5, v6, 7 bitop3:0x6c
	v_lshlrev_b32_e32 v6, 3, v6
	v_lshl_or_b32 v4, v4, 7, v6
	v_bfe_u32 v6, v12, 2, 2
	v_and_or_b32 v5, v5, s90, v6
	v_lshrrev_b32_e32 v6, 1, v12
	s_or_b32 s92, s1, 3
	s_add_i32 s95, s95, 0x20400
	v_and_b32_e32 v6, 8, v6
	s_lshl_b32 s3, s3, 10
	s_add_i32 s86, s2, s9
	s_lshl_b32 s1, s92, 14
	v_or3_b32 v5, v5, v6, v7
	v_lshlrev_b32_e32 v15, 3, v12
	s_add_u32 s80, s74, s1
	v_lshlrev_b32_e32 v5, 7, v5
	v_and_b32_e32 v6, 0x60, v12
	v_and_b32_e32 v7, 24, v15
	s_addc_u32 s81, s75, 0
	v_or3_b32 v6, v5, v6, v7
	v_ashrrev_i32_e32 v5, 31, v4
	s_add_u32 s96, s76, s1
	v_lshlrev_b64 v[4:5], 1, v[4:5]
	s_addc_u32 s97, s77, 0
	s_add_i32 s8, s3, 0
	v_lshl_add_u64 v[8:9], s[80:81], 0, v[4:5]
	v_ashrrev_i32_e32 v7, 31, v6
	s_add_i32 m0, s8, 0x1c000
	v_lshlrev_b64 v[6:7], 1, v[6:7]
	global_load_lds_dwordx4 v[8:9], off
	v_lshl_add_u64 v[8:9], v[8:9], 0, s[84:85]
	s_add_i32 m0, s8, 0x1e000
	v_lshl_add_u64 v[10:11], s[96:97], 0, v[6:7]
	global_load_lds_dwordx4 v[8:9], off
	s_add_i32 m0, s8, 0xc000
	s_or_b32 s1, s0, 0x8000
	global_load_lds_dwordx4 v[10:11], off
	s_add_i32 m0, s8, 0xe000
	s_add_u32 s82, s74, s1
	s_addc_u32 s83, s75, 0
	v_lshl_add_u64 v[8:9], v[10:11], 0, s[84:85]
	s_add_u32 s88, s76, s1
	global_load_lds_dwordx4 v[8:9], off
	v_lshl_add_u64 v[8:9], s[82:83], 0, v[4:5]
	s_addc_u32 s89, s77, 0
	s_add_i32 m0, s8, 0x18000
	v_lshl_add_u64 v[10:11], s[88:89], 0, v[6:7]
	global_load_lds_dwordx4 v[8:9], off
	v_lshl_add_u64 v[8:9], v[8:9], 0, s[84:85]
	s_add_i32 m0, s8, 0x1a000
	v_lshl_add_u64 v[148:149], s[74:75], 0, v[4:5]
	global_load_lds_dwordx4 v[8:9], off
	s_add_i32 m0, s8, 0x8000
	v_lshl_add_u64 v[8:9], v[10:11], 0, s[84:85]
	global_load_lds_dwordx4 v[10:11], off
	s_add_i32 m0, s8, 0xa000
	v_lshlrev_b32_e32 v5, 4, v12
	global_load_lds_dwordx4 v[8:9], off
	v_lshl_add_u64 v[150:151], s[76:77], 0, v[6:7]
	v_lshlrev_b32_e32 v4, 1, v12
	v_and_b32_e32 v6, 0xc0, v5
	v_and_b32_e32 v5, 0x70, v5
	s_movk_i32 s3, 0x80
	v_and_b32_e32 v4, 32, v4
	v_bitop3_b32 v153, v2, v5, s3 bitop3:0x36
	s_movk_i32 s3, 0xa0
	v_and_or_b32 v4, v15, s93, v4
	v_bitop3_b32 v155, v2, v5, s3 bitop3:0x36
	s_movk_i32 s3, 0xc0
	s_addk_i32 s2, 0xff40
	v_and_b32_e32 v8, 63, v12
	v_lshlrev_b32_e32 v9, 3, v14
	s_waitcnt vmcnt(0)
	v_bitop3_b32 v156, v2, v5, s3 bitop3:0x36
	s_movk_i32 s3, 0xe0
	v_add3_u32 v158, v6, 0, v4
	v_or_b32_e32 v4, s2, v13
	v_mov_b32_e32 v18, v3
	v_mov_b32_e32 v19, v3
	v_lshlrev_b32_e32 v152, 8, v13
	v_bitop3_b32 v157, v2, v5, s3 bitop3:0x36
	v_cmp_gt_u32_e64 s[10:11], 32, v8
	v_lshl_add_u32 v154, v13, 2, s95
	v_sub_u32_e32 v159, v4, v9
	v_mov_b32_e32 v4, v3
	v_mov_b32_e32 v5, v3
	v_mov_b32_e32 v6, v3
	v_mov_b32_e32 v7, v3
	v_mov_b32_e32 v8, v3
	v_mov_b32_e32 v9, v3
	v_mov_b32_e32 v10, v3
	v_mov_b32_e32 v11, v3
	v_mov_b32_e32 v12, v3
	v_mov_b32_e32 v13, v3
	v_mov_b32_e32 v14, v3
	v_mov_b32_e32 v15, v3
	v_mov_b32_e32 v16, v3
	v_mov_b32_e32 v17, v3
	v_mov_b64_e32 v[34:35], v[18:19]
	v_mov_b64_e32 v[50:51], v[18:19]
	v_mov_b64_e32 v[66:67], v[18:19]
	s_add_i32 s1, s8, 0x10000
	s_or_b32 s90, s86, 31
	v_mov_b32_e32 v161, 0
	v_mov_b32_e32 v160, 0xf149f2ca
	v_mov_b32_e32 v240, 0xf149f2ca
	v_mov_b64_e32 v[184:185], 0
	v_mov_b64_e32 v[186:187], 0
	v_mov_b64_e32 v[188:189], 0
	v_mov_b64_e32 v[190:191], 0
	v_mov_b64_e32 v[192:193], 0
	v_mov_b64_e32 v[194:195], 0
	v_mov_b64_e32 v[196:197], 0
	v_mov_b64_e32 v[198:199], 0
	s_mov_b32 s2, s9
	s_mov_b32 s33, s0
	v_mov_b64_e32 v[32:33], v[16:17]
	v_mov_b64_e32 v[30:31], v[14:15]
	v_mov_b64_e32 v[28:29], v[12:13]
	v_mov_b64_e32 v[26:27], v[10:11]
	v_mov_b64_e32 v[24:25], v[8:9]
	v_mov_b64_e32 v[22:23], v[6:7]
	v_mov_b64_e32 v[20:21], v[4:5]
	v_mov_b64_e32 v[48:49], v[16:17]
	v_mov_b64_e32 v[46:47], v[14:15]
	v_mov_b64_e32 v[44:45], v[12:13]
	v_mov_b64_e32 v[42:43], v[10:11]
	v_mov_b64_e32 v[40:41], v[8:9]
	v_mov_b64_e32 v[38:39], v[6:7]
	v_mov_b64_e32 v[36:37], v[4:5]
	v_mov_b64_e32 v[64:65], v[16:17]
	v_mov_b64_e32 v[62:63], v[14:15]
	v_mov_b64_e32 v[60:61], v[12:13]
	v_mov_b64_e32 v[58:59], v[10:11]
	v_mov_b64_e32 v[56:57], v[8:9]
	v_mov_b64_e32 v[54:55], v[6:7]
	v_mov_b64_e32 v[52:53], v[4:5]
	s_mov_b32 s94, s92
	s_waitcnt vmcnt(0) lgkmcnt(0)
	s_barrier
	s_branch .LBB0_917

.LBB0_921:
	s_add_i32 s4, s33, 0xc000
	s_and_b32 s4, s4, 0xc000
	s_add_i32 s12, s4, 0
	s_add_i32 s12, s12, 0x10000
	v_add_u32_e32 v76, s12, v152
	v_add_u32_e32 v77, v76, v153
	ds_read_b128 v[68:71], v77 offset:0
	ds_read_b128 v[72:75], v77 offset:0x2000
	v_add_u32_e32 v77, v76, v155
	ds_read_b128 v[116:119], v77 offset:0
	ds_read_b128 v[120:123], v77 offset:0x2000
	v_add_u32_e32 v77, v76, v156
	ds_read_b128 v[124:127], v77 offset:0
	ds_read_b128 v[128:131], v77 offset:0x2000
	v_add_u32_e32 v76, v76, v157
	ds_read_b128 v[132:135], v76 offset:0
	ds_read_b128 v[136:139], v76 offset:0x2000
	s_waitcnt lgkmcnt(4)
	s_add_i32 s3, s2, 0xff
	s_cmp_le_u32 s3, s86
	v_mfma_f32_32x32x16_bf16 v[84:99], v[68:71], v[100:103], v[184:199]
	v_mfma_f32_32x32x16_bf16 v[84:99], v[116:119], v[104:107], v[84:99]
	v_mfma_f32_32x32x16_bf16 v[68:83], v[72:75], v[100:103], v[184:199]
	v_mfma_f32_32x32x16_bf16 v[68:83], v[120:123], v[104:107], v[68:83]
	s_waitcnt lgkmcnt(0)
	v_mfma_f32_32x32x16_bf16 v[84:99], v[124:127], v[108:111], v[84:99]
	v_mfma_f32_32x32x16_bf16 v[84:99], v[132:135], v[112:115], v[84:99]
	v_mfma_f32_32x32x16_bf16 v[68:83], v[128:131], v[108:111], v[68:83]
	v_mfma_f32_32x32x16_bf16 v[68:83], v[136:139], v[112:115], v[68:83]
	v_add_u32_e32 v162, s4, v158
	ds_read_b64_tr_b16 v[144:145], v162 offset:0
	ds_read_b64_tr_b16 v[146:147], v162 offset:0x800
	ds_read_b64_tr_b16 v[140:141], v162 offset:0x1000
	ds_read_b64_tr_b16 v[142:143], v162 offset:0x1800
	ds_read_b64_tr_b16 v[136:137], v162 offset:0x2000
	ds_read_b64_tr_b16 v[138:139], v162 offset:0x2800
	ds_read_b64_tr_b16 v[132:133], v162 offset:0x3000
	ds_read_b64_tr_b16 v[134:135], v162 offset:0x3800
	ds_read_b64_tr_b16 v[128:129], v162 offset:0x200
	ds_read_b64_tr_b16 v[130:131], v162 offset:0xa00
	ds_read_b64_tr_b16 v[124:125], v162 offset:0x1200
	ds_read_b64_tr_b16 v[126:127], v162 offset:0x1a00
	ds_read_b64_tr_b16 v[120:121], v162 offset:0x2200
	ds_read_b64_tr_b16 v[122:123], v162 offset:0x2a00
	ds_read_b64_tr_b16 v[116:117], v162 offset:0x3200
	ds_read_b64_tr_b16 v[118:119], v162 offset:0x3a00
	s_cbranch_scc1 .LBB0_923
	v_cmp_gt_i32_e64 s[70:71], 22, v159
	v_cmp_gt_i32_e64 s[72:73], 23, v159
	v_cmp_gt_i32_e64 s[68:69], 21, v159
	s_and_b64 s[70:71], s[72:73], s[70:71]
	v_cmp_gt_i32_e64 s[66:67], 20, v159
	s_and_b64 s[68:69], s[70:71], s[68:69]
	v_cmp_gt_i32_e64 s[64:65], 19, v159
	s_and_b64 s[66:67], s[68:69], s[66:67]
	v_cmp_gt_i32_e64 s[62:63], 18, v159
	s_and_b64 s[64:65], s[66:67], s[64:65]
	v_cmp_gt_i32_e64 s[60:61], 17, v159
	s_and_b64 s[62:63], s[64:65], s[62:63]
	v_cmp_gt_i32_e64 s[58:59], 16, v159
	s_and_b64 s[60:61], s[62:63], s[60:61]
	v_cmp_gt_i32_e64 s[56:57], 7, v159
	s_and_b64 s[58:59], s[60:61], s[58:59]
	v_cmp_gt_i32_e64 s[54:55], 6, v159
	s_and_b64 s[56:57], s[58:59], s[56:57]
	v_cmp_gt_i32_e64 s[52:53], 5, v159
	s_and_b64 s[54:55], s[56:57], s[54:55]
	v_cmp_gt_i32_e64 s[50:51], 4, v159
	s_and_b64 s[52:53], s[54:55], s[52:53]
	v_cmp_gt_i32_e64 s[48:49], 3, v159
	s_and_b64 s[50:51], s[52:53], s[50:51]
	v_cmp_gt_i32_e64 s[46:47], 2, v159
	s_and_b64 s[48:49], s[50:51], s[48:49]
	v_cmp_gt_i32_e64 s[44:45], 1, v159
	s_and_b64 s[46:47], s[48:49], s[46:47]
	v_cmp_gt_i32_e64 s[42:43], 0, v159
	s_and_b64 s[44:45], s[46:47], s[44:45]
	s_and_b64 s[42:43], s[44:45], s[42:43]
	v_cmp_gt_i32_e64 s[40:41], 54, v159
	v_cndmask_b32_e64 v84, v84, v204, s[42:43]
	v_cmp_gt_i32_e64 s[42:43], 55, v159
	v_cmp_gt_i32_e64 s[38:39], 53, v159
	s_and_b64 s[40:41], s[42:43], s[40:41]
	v_cmp_gt_i32_e64 s[36:37], 52, v159
	s_and_b64 s[38:39], s[40:41], s[38:39]
	v_cmp_gt_i32_e64 s[34:35], 51, v159
	s_and_b64 s[36:37], s[38:39], s[36:37]
	v_cmp_gt_i32_e64 s[30:31], 50, v159
	s_and_b64 s[34:35], s[36:37], s[34:35]
	v_cmp_gt_i32_e64 s[28:29], 49, v159
	s_and_b64 s[30:31], s[34:35], s[30:31]
	v_cmp_gt_i32_e64 s[26:27], 48, v159
	s_and_b64 s[28:29], s[30:31], s[28:29]
	v_cmp_gt_i32_e64 s[24:25], 39, v159
	s_and_b64 s[26:27], s[28:29], s[26:27]
	v_cmp_gt_i32_e64 s[22:23], 38, v159
	s_and_b64 s[24:25], s[26:27], s[24:25]
	v_cmp_gt_i32_e64 s[20:21], 37, v159
	s_and_b64 s[22:23], s[24:25], s[22:23]
	v_cmp_gt_i32_e64 s[18:19], 36, v159
	s_and_b64 s[20:21], s[22:23], s[20:21]
	v_cmp_gt_i32_e64 s[16:17], 35, v159
	s_and_b64 s[18:19], s[20:21], s[18:19]
	v_cmp_gt_i32_e64 s[14:15], 34, v159
	s_and_b64 s[16:17], s[18:19], s[16:17]
	v_cmp_gt_i32_e64 s[12:13], 33, v159
	s_and_b64 s[14:15], s[16:17], s[14:15]
	v_cmp_gt_i32_e32 vcc, 32, v159
	s_and_b64 s[12:13], s[14:15], s[12:13]
	s_and_b64 vcc, s[12:13], vcc
	v_cndmask_b32_e64 v99, v99, v204, s[72:73]
	v_cndmask_b32_e64 v98, v98, v204, s[70:71]
	v_cndmask_b32_e64 v97, v97, v204, s[68:69]
	v_cndmask_b32_e64 v96, v96, v204, s[66:67]
	v_cndmask_b32_e64 v95, v95, v204, s[64:65]
	v_cndmask_b32_e64 v94, v94, v204, s[62:63]
	v_cndmask_b32_e64 v93, v93, v204, s[60:61]
	v_cndmask_b32_e64 v92, v92, v204, s[58:59]
	v_cndmask_b32_e64 v91, v91, v204, s[56:57]
	v_cndmask_b32_e64 v90, v90, v204, s[54:55]
	v_cndmask_b32_e64 v89, v89, v204, s[52:53]
	v_cndmask_b32_e64 v88, v88, v204, s[50:51]
	v_cndmask_b32_e64 v87, v87, v204, s[48:49]
	v_cndmask_b32_e64 v86, v86, v204, s[46:47]
	v_cndmask_b32_e64 v85, v85, v204, s[44:45]
	v_cndmask_b32_e64 v83, v83, v204, s[42:43]
	v_cndmask_b32_e64 v82, v82, v204, s[40:41]
	v_cndmask_b32_e64 v81, v81, v204, s[38:39]
	v_cndmask_b32_e64 v80, v80, v204, s[36:37]
	v_cndmask_b32_e64 v79, v79, v204, s[34:35]
	v_cndmask_b32_e64 v78, v78, v204, s[30:31]
	v_cndmask_b32_e64 v77, v77, v204, s[28:29]
	v_cndmask_b32_e64 v76, v76, v204, s[26:27]
	v_cndmask_b32_e64 v75, v75, v204, s[24:25]
	v_cndmask_b32_e64 v74, v74, v204, s[22:23]
	v_cndmask_b32_e64 v73, v73, v204, s[20:21]
	v_cndmask_b32_e64 v72, v72, v204, s[18:19]
	v_cndmask_b32_e64 v71, v71, v204, s[16:17]
	v_cndmask_b32_e64 v70, v70, v204, s[14:15]
	v_cndmask_b32_e64 v69, v69, v204, s[12:13]
	v_cndmask_b32_e32 v68, v68, v204, vcc
.LBB0_923:
	s_nop 8
	v_max_f32_e32 v163, v84, v85
	v_max3_f32 v163, v163, v86, v87
	v_max3_f32 v163, v163, v88, v89
	v_max3_f32 v163, v163, v90, v91
	v_max3_f32 v163, v163, v92, v93
	v_max3_f32 v163, v163, v94, v95
	v_max3_f32 v163, v163, v96, v97
	v_max3_f32 v163, v163, v98, v99
	v_max3_f32 v163, v163, v68, v69
	v_max3_f32 v163, v163, v70, v71
	v_max3_f32 v163, v163, v72, v73
	v_max3_f32 v163, v163, v74, v75
	v_max3_f32 v163, v163, v76, v77
	v_max3_f32 v163, v163, v78, v79
	v_max3_f32 v163, v163, v80, v81
	v_max3_f32 v163, v163, v82, v83
	v_mov_b32_e32 v164, v163
	s_nop 1
	v_permlane32_swap_b32_e32 v163, v164
	v_max_f32_e32 v164, v163, v164
	v_sub_f32_e32 v163, v164, v240
	v_cmp_ge_f32_e32 vcc, s91, v163
	s_cmp_eq_u64 vcc, exec
	v_mov_b32_e32 v163, 1.0
	s_cbranch_scc0 .LBB0_935
.LBB0_924:
	v_exp_f32_e32 v164, v84
	v_exp_f32_e32 v85, v85
	v_exp_f32_e32 v86, v86
	v_exp_f32_e32 v87, v87
	v_exp_f32_e32 v88, v88
	v_exp_f32_e32 v89, v89
	v_exp_f32_e32 v90, v90
	v_exp_f32_e32 v165, v91
	v_exp_f32_e32 v84, v75
	v_exp_f32_e32 v91, v92
	v_exp_f32_e32 v92, v93
	v_exp_f32_e32 v93, v94
	v_exp_f32_e32 v94, v95
	v_exp_f32_e32 v95, v96
	v_exp_f32_e32 v96, v97
	v_exp_f32_e32 v97, v98
	v_exp_f32_e32 v98, v99
	v_mov_b32_e32 v243, v83
	v_add_f32_e32 v83, 0, v164
	v_add_f32_e32 v83, v85, v83
	v_add_f32_e32 v83, v86, v83
	v_add_f32_e32 v83, v87, v83
	v_add_f32_e32 v83, v88, v83
	v_add_f32_e32 v83, v89, v83
	v_add_f32_e32 v83, v90, v83
	v_add_f32_e32 v83, v165, v83
	v_add_f32_e32 v83, v91, v83
	v_add_f32_e32 v83, v92, v83
	v_add_f32_e32 v83, v93, v83
	v_add_f32_e32 v83, v94, v83
	v_exp_f32_e32 v68, v68
	v_add_f32_e32 v83, v95, v83
	v_exp_f32_e32 v69, v69
	v_add_f32_e32 v83, v96, v83
	v_exp_f32_e32 v70, v70
	v_add_f32_e32 v83, v97, v83
	v_exp_f32_e32 v71, v71
	v_add_f32_e32 v83, v98, v83
	v_exp_f32_e32 v72, v72
	v_add_f32_e32 v83, v68, v83
	v_exp_f32_e32 v73, v73
	v_add_f32_e32 v83, v69, v83
	v_exp_f32_e32 v74, v74
	v_add_f32_e32 v83, v70, v83
	v_add_f32_e32 v83, v71, v83
	v_exp_f32_e32 v75, v76
	v_add_f32_e32 v83, v72, v83
	v_exp_f32_e32 v76, v77
	v_add_f32_e32 v83, v73, v83
	v_exp_f32_e32 v77, v78
	v_add_f32_e32 v83, v74, v83
	v_exp_f32_e32 v78, v79
	v_add_f32_e32 v83, v84, v83
	v_exp_f32_e32 v79, v80
	v_add_f32_e32 v83, v75, v83
	v_exp_f32_e32 v80, v81
	v_add_f32_e32 v83, v76, v83
	v_exp_f32_e32 v81, v82
	v_add_f32_e32 v83, v77, v83
	v_exp_f32_e32 v82, v243
	v_add_f32_e32 v83, v78, v83
	v_add_f32_e32 v83, v79, v83
	v_add_f32_e32 v83, v80, v83
	v_add_f32_e32 v83, v81, v83
	v_add_f32_e32 v83, v82, v83
	v_mov_b32_e32 v99, v83
	s_nop 1
	v_permlane32_swap_b32_e32 v83, v99
	v_cmp_gt_f32_e32 vcc, 1.0, v163
	s_cbranch_vccz .LBB0_928
	s_and_saveexec_b64 s[12:13], s[10:11]
	ds_write_b32 v154, v163 offset:128
	s_or_b64 exec, exec, s[12:13]
	s_waitcnt lgkmcnt(0)
	v_add_u32_e32 v178, s95, v2
	ds_read_b128 v[166:169], v178 offset:224
	ds_read_b128 v[170:173], v178 offset:192
	ds_read_b128 v[174:177], v178 offset:160
	ds_read_b128 v[178:181], v178 offset:128
	s_waitcnt lgkmcnt(0)
	s_waitcnt lgkmcnt(0)
	v_pk_mul_f32 v[64:65], v[166:167], v[64:65]
	v_pk_mul_f32 v[60:61], v[170:171], v[60:61]
	v_pk_mul_f32 v[56:57], v[174:175], v[56:57]
	v_pk_mul_f32 v[66:67], v[168:169], v[66:67]
	v_pk_mul_f32 v[62:63], v[172:173], v[62:63]
	v_pk_mul_f32 v[58:59], v[176:177], v[58:59]
	v_pk_mul_f32 v[54:55], v[180:181], v[54:55]
	v_pk_mul_f32 v[52:53], v[178:179], v[52:53]
	v_pk_mul_f32 v[48:49], v[166:167], v[48:49]
	v_pk_mul_f32 v[44:45], v[170:171], v[44:45]
	v_pk_mul_f32 v[40:41], v[174:175], v[40:41]
	v_pk_mul_f32 v[50:51], v[168:169], v[50:51]
	v_pk_mul_f32 v[46:47], v[172:173], v[46:47]
	v_pk_mul_f32 v[42:43], v[176:177], v[42:43]
	v_pk_mul_f32 v[38:39], v[180:181], v[38:39]
	v_pk_mul_f32 v[36:37], v[178:179], v[36:37]
	v_pk_mul_f32 v[32:33], v[166:167], v[32:33]
	v_pk_mul_f32 v[28:29], v[170:171], v[28:29]
	v_pk_mul_f32 v[24:25], v[174:175], v[24:25]
	v_pk_mul_f32 v[34:35], v[168:169], v[34:35]
	v_pk_mul_f32 v[30:31], v[172:173], v[30:31]
	v_pk_mul_f32 v[26:27], v[176:177], v[26:27]
	v_pk_mul_f32 v[22:23], v[180:181], v[22:23]
	v_pk_mul_f32 v[20:21], v[178:179], v[20:21]
	v_pk_mul_f32 v[16:17], v[166:167], v[16:17]
	v_pk_mul_f32 v[12:13], v[170:171], v[12:13]
	v_pk_mul_f32 v[8:9], v[174:175], v[8:9]
	v_pk_mul_f32 v[18:19], v[168:169], v[18:19]
	v_pk_mul_f32 v[14:15], v[172:173], v[14:15]
	v_pk_mul_f32 v[10:11], v[176:177], v[10:11]
	v_pk_mul_f32 v[6:7], v[180:181], v[6:7]
	v_pk_mul_f32 v[4:5], v[178:179], v[4:5]

.LBB0_929:
	s_add_i32 s4, s33, 0x8000
	s_and_b32 s4, s4, 0xc000
	s_add_i32 s12, s4, 0
	s_add_i32 s12, s12, 0x10000
	v_add_u32_e32 v76, s12, v152
	v_add_u32_e32 v77, v76, v153
	ds_read_b128 v[68:71], v77 offset:0
	ds_read_b128 v[72:75], v77 offset:0x2000
	v_add_u32_e32 v77, v76, v155
	ds_read_b128 v[116:119], v77 offset:0
	ds_read_b128 v[120:123], v77 offset:0x2000
	v_add_u32_e32 v77, v76, v156
	ds_read_b128 v[124:127], v77 offset:0
	ds_read_b128 v[128:131], v77 offset:0x2000
	v_add_u32_e32 v76, v76, v157
	ds_read_b128 v[132:135], v76 offset:0
	ds_read_b128 v[136:139], v76 offset:0x2000
	s_waitcnt lgkmcnt(4)
	s_add_i32 s3, s2, 0xbf
	s_cmp_le_i32 s3, s86
	v_mfma_f32_32x32x16_bf16 v[84:99], v[68:71], v[100:103], v[184:199]
	v_mfma_f32_32x32x16_bf16 v[84:99], v[116:119], v[104:107], v[84:99]
	v_mfma_f32_32x32x16_bf16 v[68:83], v[72:75], v[100:103], v[184:199]
	v_mfma_f32_32x32x16_bf16 v[68:83], v[120:123], v[104:107], v[68:83]
	s_waitcnt lgkmcnt(0)
	v_mfma_f32_32x32x16_bf16 v[84:99], v[124:127], v[108:111], v[84:99]
	v_mfma_f32_32x32x16_bf16 v[84:99], v[132:135], v[112:115], v[84:99]
	v_mfma_f32_32x32x16_bf16 v[68:83], v[128:131], v[108:111], v[68:83]
	v_mfma_f32_32x32x16_bf16 v[68:83], v[136:139], v[112:115], v[68:83]
	v_add_u32_e32 v162, s4, v158
	ds_read_b64_tr_b16 v[144:145], v162 offset:0
	ds_read_b64_tr_b16 v[146:147], v162 offset:0x800
	ds_read_b64_tr_b16 v[140:141], v162 offset:0x1000
	ds_read_b64_tr_b16 v[142:143], v162 offset:0x1800
	ds_read_b64_tr_b16 v[136:137], v162 offset:0x2000
	ds_read_b64_tr_b16 v[138:139], v162 offset:0x2800
	ds_read_b64_tr_b16 v[132:133], v162 offset:0x3000
	ds_read_b64_tr_b16 v[134:135], v162 offset:0x3800
	ds_read_b64_tr_b16 v[128:129], v162 offset:0x200
	ds_read_b64_tr_b16 v[130:131], v162 offset:0xa00
	ds_read_b64_tr_b16 v[124:125], v162 offset:0x1200
	ds_read_b64_tr_b16 v[126:127], v162 offset:0x1a00
	ds_read_b64_tr_b16 v[120:121], v162 offset:0x2200
	ds_read_b64_tr_b16 v[122:123], v162 offset:0x2a00
	ds_read_b64_tr_b16 v[116:117], v162 offset:0x3200
	ds_read_b64_tr_b16 v[118:119], v162 offset:0x3a00
	s_cbranch_scc1 .LBB0_931
	v_add_u32_e32 v163, 64, v159
	v_cmp_gt_i32_e64 s[70:71], 22, v163
	v_cmp_gt_i32_e64 s[72:73], 23, v163
	v_cmp_gt_i32_e64 s[68:69], 21, v163
	s_and_b64 s[70:71], s[72:73], s[70:71]
	v_cmp_gt_i32_e64 s[66:67], 20, v163
	s_and_b64 s[68:69], s[70:71], s[68:69]
	v_cmp_gt_i32_e64 s[64:65], 19, v163
	s_and_b64 s[66:67], s[68:69], s[66:67]
	v_cmp_gt_i32_e64 s[62:63], 18, v163
	s_and_b64 s[64:65], s[66:67], s[64:65]
	v_cmp_gt_i32_e64 s[60:61], 17, v163
	s_and_b64 s[62:63], s[64:65], s[62:63]
	v_cmp_gt_i32_e64 s[58:59], 16, v163
	s_and_b64 s[60:61], s[62:63], s[60:61]
	v_cmp_gt_i32_e64 s[56:57], 7, v163
	s_and_b64 s[58:59], s[60:61], s[58:59]
	v_cmp_gt_i32_e64 s[54:55], 6, v163
	s_and_b64 s[56:57], s[58:59], s[56:57]
	v_cmp_gt_i32_e64 s[52:53], 5, v163
	s_and_b64 s[54:55], s[56:57], s[54:55]
	v_cmp_gt_i32_e64 s[50:51], 4, v163
	s_and_b64 s[52:53], s[54:55], s[52:53]
	v_cmp_gt_i32_e64 s[48:49], 3, v163
	s_and_b64 s[50:51], s[52:53], s[50:51]
	v_cmp_gt_i32_e64 s[46:47], 2, v163
	s_and_b64 s[48:49], s[50:51], s[48:49]
	v_cmp_gt_i32_e64 s[44:45], 1, v163
	s_and_b64 s[46:47], s[48:49], s[46:47]
	v_cmp_gt_i32_e64 s[42:43], 0, v163
	s_and_b64 s[44:45], s[46:47], s[44:45]
	s_and_b64 s[42:43], s[44:45], s[42:43]
	v_cmp_gt_i32_e64 s[40:41], 54, v163
	v_cndmask_b32_e64 v84, v84, v204, s[42:43]
	v_cmp_gt_i32_e64 s[42:43], 55, v163
	v_cmp_gt_i32_e64 s[38:39], 53, v163
	s_and_b64 s[40:41], s[42:43], s[40:41]
	v_cmp_gt_i32_e64 s[36:37], 52, v163
	s_and_b64 s[38:39], s[40:41], s[38:39]
	v_cmp_gt_i32_e64 s[34:35], 51, v163
	s_and_b64 s[36:37], s[38:39], s[36:37]
	v_cmp_gt_i32_e64 s[30:31], 50, v163
	s_and_b64 s[34:35], s[36:37], s[34:35]
	v_cmp_gt_i32_e64 s[28:29], 49, v163
	s_and_b64 s[30:31], s[34:35], s[30:31]
	v_cmp_gt_i32_e64 s[26:27], 48, v163
	s_and_b64 s[28:29], s[30:31], s[28:29]
	v_cmp_gt_i32_e64 s[24:25], 39, v163
	s_and_b64 s[26:27], s[28:29], s[26:27]
	v_cmp_gt_i32_e64 s[22:23], 38, v163
	s_and_b64 s[24:25], s[26:27], s[24:25]
	v_cmp_gt_i32_e64 s[20:21], 37, v163
	s_and_b64 s[22:23], s[24:25], s[22:23]
	v_cmp_gt_i32_e64 s[18:19], 36, v163
	s_and_b64 s[20:21], s[22:23], s[20:21]
	v_cmp_gt_i32_e64 s[16:17], 35, v163
	s_and_b64 s[18:19], s[20:21], s[18:19]
	v_cmp_gt_i32_e64 s[14:15], 34, v163
	s_and_b64 s[16:17], s[18:19], s[16:17]
	v_cmp_gt_i32_e64 s[12:13], 33, v163
	s_and_b64 s[14:15], s[16:17], s[14:15]
	v_cmp_gt_i32_e32 vcc, 32, v163
	s_and_b64 s[12:13], s[14:15], s[12:13]
	s_and_b64 vcc, s[12:13], vcc
	v_cndmask_b32_e64 v99, v99, v204, s[72:73]
	v_cndmask_b32_e64 v98, v98, v204, s[70:71]
	v_cndmask_b32_e64 v97, v97, v204, s[68:69]
	v_cndmask_b32_e64 v96, v96, v204, s[66:67]
	v_cndmask_b32_e64 v95, v95, v204, s[64:65]
	v_cndmask_b32_e64 v94, v94, v204, s[62:63]
	v_cndmask_b32_e64 v93, v93, v204, s[60:61]
	v_cndmask_b32_e64 v92, v92, v204, s[58:59]
	v_cndmask_b32_e64 v91, v91, v204, s[56:57]
	v_cndmask_b32_e64 v90, v90, v204, s[54:55]
	v_cndmask_b32_e64 v89, v89, v204, s[52:53]
	v_cndmask_b32_e64 v88, v88, v204, s[50:51]
	v_cndmask_b32_e64 v87, v87, v204, s[48:49]
	v_cndmask_b32_e64 v86, v86, v204, s[46:47]
	v_cndmask_b32_e64 v85, v85, v204, s[44:45]
	v_cndmask_b32_e64 v83, v83, v204, s[42:43]
	v_cndmask_b32_e64 v82, v82, v204, s[40:41]
	v_cndmask_b32_e64 v81, v81, v204, s[38:39]
	v_cndmask_b32_e64 v80, v80, v204, s[36:37]
	v_cndmask_b32_e64 v79, v79, v204, s[34:35]
	v_cndmask_b32_e64 v78, v78, v204, s[30:31]
	v_cndmask_b32_e64 v77, v77, v204, s[28:29]
	v_cndmask_b32_e64 v76, v76, v204, s[26:27]
	v_cndmask_b32_e64 v75, v75, v204, s[24:25]
	v_cndmask_b32_e64 v74, v74, v204, s[22:23]
	v_cndmask_b32_e64 v73, v73, v204, s[20:21]
	v_cndmask_b32_e64 v72, v72, v204, s[18:19]
	v_cndmask_b32_e64 v71, v71, v204, s[16:17]
	v_cndmask_b32_e64 v70, v70, v204, s[14:15]
	v_cndmask_b32_e64 v69, v69, v204, s[12:13]
	v_cndmask_b32_e32 v68, v68, v204, vcc

.LBB0_932:
	v_exp_f32_e32 v164, v84
	v_exp_f32_e32 v85, v85
	v_exp_f32_e32 v86, v86
	v_exp_f32_e32 v87, v87
	v_exp_f32_e32 v88, v88
	v_exp_f32_e32 v89, v89
	v_exp_f32_e32 v90, v90
	v_exp_f32_e32 v165, v91
	v_exp_f32_e32 v84, v75
	v_exp_f32_e32 v91, v92
	v_exp_f32_e32 v92, v93
	v_exp_f32_e32 v93, v94
	v_exp_f32_e32 v94, v95
	v_exp_f32_e32 v95, v96
	v_exp_f32_e32 v96, v97
	v_exp_f32_e32 v97, v98
	v_exp_f32_e32 v98, v99
	v_mov_b32_e32 v243, v83
	v_add_f32_e32 v83, 0, v164
	v_add_f32_e32 v83, v85, v83
	v_add_f32_e32 v83, v86, v83
	v_add_f32_e32 v83, v87, v83
	v_add_f32_e32 v83, v88, v83
	v_add_f32_e32 v83, v89, v83
	v_add_f32_e32 v83, v90, v83
	v_add_f32_e32 v83, v165, v83
	v_add_f32_e32 v83, v91, v83
	v_add_f32_e32 v83, v92, v83
	v_add_f32_e32 v83, v93, v83
	v_add_f32_e32 v83, v94, v83
	v_exp_f32_e32 v68, v68
	v_add_f32_e32 v83, v95, v83
	v_exp_f32_e32 v69, v69
	v_add_f32_e32 v83, v96, v83
	v_exp_f32_e32 v70, v70
	v_add_f32_e32 v83, v97, v83
	v_exp_f32_e32 v71, v71
	v_add_f32_e32 v83, v98, v83
	v_exp_f32_e32 v72, v72
	v_add_f32_e32 v83, v68, v83
	v_exp_f32_e32 v73, v73
	v_add_f32_e32 v83, v69, v83
	v_exp_f32_e32 v74, v74
	v_add_f32_e32 v83, v70, v83
	v_add_f32_e32 v83, v71, v83
	v_exp_f32_e32 v75, v76
	v_add_f32_e32 v83, v72, v83
	v_exp_f32_e32 v76, v77
	v_add_f32_e32 v83, v73, v83
	v_exp_f32_e32 v77, v78
	v_add_f32_e32 v83, v74, v83
	v_exp_f32_e32 v78, v79
	v_add_f32_e32 v83, v84, v83
	v_exp_f32_e32 v79, v80
	v_add_f32_e32 v83, v75, v83
	v_exp_f32_e32 v80, v81
	v_add_f32_e32 v83, v76, v83
	v_exp_f32_e32 v81, v82
	v_add_f32_e32 v83, v77, v83
	v_exp_f32_e32 v82, v243
	v_add_f32_e32 v83, v78, v83
	v_add_f32_e32 v83, v79, v83
	v_add_f32_e32 v83, v80, v83
	v_add_f32_e32 v83, v81, v83
	v_add_f32_e32 v83, v82, v83
	v_mov_b32_e32 v99, v83
	s_nop 1
	v_permlane32_swap_b32_e32 v83, v99
	v_cmp_gt_f32_e32 vcc, 1.0, v163
	s_cbranch_vccz .LBB0_915
	s_and_saveexec_b64 s[12:13], s[10:11]
	s_cbranch_execz .LBB0_914
	ds_write_b32 v154, v163 offset:128
	s_branch .LBB0_914
.LBB0_935:
	v_sub_f32_e32 v241, v164, v184
	v_max_f32_e32 v241, v160, v241
	v_sub_f32_e32 v163, v160, v241
	v_exp_f32_e32 v163, v163
	v_add_f32_e32 v242, v241, v184
	v_mov_b32_e32 v160, v241
	v_sub_f32_e32 v84, v84, v242
	v_sub_f32_e32 v85, v85, v242
	v_sub_f32_e32 v86, v86, v242
	v_sub_f32_e32 v87, v87, v242
	v_sub_f32_e32 v88, v88, v242
	v_sub_f32_e32 v89, v89, v242
	v_sub_f32_e32 v90, v90, v242
	v_sub_f32_e32 v91, v91, v242
	v_sub_f32_e32 v92, v92, v242
	v_sub_f32_e32 v93, v93, v242
	v_sub_f32_e32 v94, v94, v242
	v_sub_f32_e32 v95, v95, v242
	v_sub_f32_e32 v96, v96, v242
	v_sub_f32_e32 v97, v97, v242
	v_sub_f32_e32 v98, v98, v242
	v_sub_f32_e32 v99, v99, v242
	v_sub_f32_e32 v68, v68, v242
	v_sub_f32_e32 v69, v69, v242
	v_sub_f32_e32 v70, v70, v242
	v_sub_f32_e32 v71, v71, v242
	v_sub_f32_e32 v72, v72, v242
	v_sub_f32_e32 v73, v73, v242
	v_sub_f32_e32 v74, v74, v242
	v_sub_f32_e32 v75, v75, v242
	v_sub_f32_e32 v76, v76, v242
	v_sub_f32_e32 v77, v77, v242
	v_sub_f32_e32 v78, v78, v242
	v_sub_f32_e32 v79, v79, v242
	v_sub_f32_e32 v80, v80, v242
	v_sub_f32_e32 v81, v81, v242
	v_sub_f32_e32 v82, v82, v242
	v_sub_f32_e32 v83, v83, v242
	v_cmp_lt_f32_e32 vcc, 0xf0000000, v241
	v_sub_f32_e32 v242, 0, v241
	v_cndmask_b32_e32 v242, 0, v242, vcc
	v_add_f32_e32 v240, v241, v242
	v_mov_b32_e32 v184, v242
	v_mov_b32_e32 v185, v242
	v_mov_b32_e32 v186, v242
	v_mov_b32_e32 v187, v242
	v_mov_b32_e32 v188, v242
	v_mov_b32_e32 v189, v242
	v_mov_b32_e32 v190, v242
	v_mov_b32_e32 v191, v242
	v_mov_b32_e32 v192, v242
	v_mov_b32_e32 v193, v242
	v_mov_b32_e32 v194, v242
	v_mov_b32_e32 v195, v242
	v_mov_b32_e32 v196, v242
	v_mov_b32_e32 v197, v242
	v_mov_b32_e32 v198, v242
	v_mov_b32_e32 v199, v242
	s_branch .LBB0_924

.LBB0_937:
	s_and_saveexec_b64 s[2:3], s[10:11]
	ds_write_b32 v154, v161
	s_or_b64 exec, exec, s[2:3]
	s_waitcnt lgkmcnt(0)
	v_add_u32_e32 v2, s95, v2
	ds_read_b128 v[68:71], v2
	ds_read_b128 v[72:75], v2 offset:32
	v_readlane_b32 s2, v245, 62
	v_readlane_b32 s3, v245, 63
	s_mov_b32 s90, 0x1fffff0
	s_waitcnt lgkmcnt(1)
	v_rcp_f32_e32 v68, v68
	v_rcp_f32_e32 v69, v69
	v_rcp_f32_e32 v70, v70
	v_rcp_f32_e32 v71, v71
	s_waitcnt lgkmcnt(0)
	v_rcp_f32_e32 v72, v72
	v_pk_mul_f32 v[52:53], v[68:69], v[52:53]
	v_pk_mul_f32 v[36:37], v[68:69], v[36:37]
	v_pk_mul_f32 v[20:21], v[68:69], v[20:21]
	v_pk_mul_f32 v[4:5], v[68:69], v[4:5]
	v_pk_mul_f32 v[54:55], v[70:71], v[54:55]
	v_rcp_f32_e32 v73, v73
	v_pk_mul_f32 v[38:39], v[70:71], v[38:39]
	v_pk_mul_f32 v[22:23], v[70:71], v[22:23]
	v_pk_mul_f32 v[6:7], v[70:71], v[6:7]
	ds_read_b128 v[68:71], v2 offset:64
	v_pk_mul_f32 v[56:57], v[72:73], v[56:57]
	v_pk_mul_f32 v[40:41], v[72:73], v[40:41]
	v_rcp_f32_e32 v76, v74
	v_rcp_f32_e32 v77, v75
	v_pk_mul_f32 v[24:25], v[72:73], v[24:25]
	v_pk_mul_f32 v[8:9], v[72:73], v[8:9]
	ds_read_b128 v[72:75], v2 offset:96
	s_waitcnt lgkmcnt(1)
	v_rcp_f32_e32 v68, v68
	v_rcp_f32_e32 v69, v69
	v_rcp_f32_e32 v70, v70
	v_rcp_f32_e32 v71, v71
	v_mov_b32_e32 v2, v0
	v_pk_mul_f32 v[60:61], v[68:69], v[60:61]
	v_pk_mul_f32 v[44:45], v[68:69], v[44:45]
	v_pk_mul_f32 v[28:29], v[68:69], v[28:29]
	v_pk_mul_f32 v[12:13], v[68:69], v[12:13]
	s_waitcnt lgkmcnt(0)
	v_rcp_f32_e32 v68, v72
	v_rcp_f32_e32 v69, v73
	v_pk_mul_f32 v[62:63], v[70:71], v[62:63]
	v_pk_mul_f32 v[46:47], v[70:71], v[46:47]
	v_pk_mul_f32 v[30:31], v[70:71], v[30:31]
	v_pk_mul_f32 v[14:15], v[70:71], v[14:15]
	v_rcp_f32_e32 v70, v74
	v_rcp_f32_e32 v71, v75
	v_pk_mul_f32 v[64:65], v[68:69], v[64:65]
	v_pk_mul_f32 v[48:49], v[68:69], v[48:49]
	v_pk_mul_f32 v[32:33], v[68:69], v[32:33]
	v_pk_mul_f32 v[16:17], v[68:69], v[16:17]
	s_waitcnt lgkmcnt(0)
	v_pk_mul_f32 v[58:59], v[76:77], v[58:59]
	v_lshlrev_b32_e32 v68, 6, v2
	v_ashrrev_i32_e32 v69, 31, v68
	v_lshl_add_u64 v[148:149], v[68:69], 2, s[2:3]
	v_pk_mul_f32 v[42:43], v[76:77], v[42:43]
	v_pk_mul_f32 v[26:27], v[76:77], v[26:27]
	v_pk_mul_f32 v[10:11], v[76:77], v[10:11]
	v_pk_mul_f32 v[66:67], v[70:71], v[66:67]
	v_pk_mul_f32 v[50:51], v[70:71], v[50:51]
	v_pk_mul_f32 v[34:35], v[70:71], v[34:35]
	v_pk_mul_f32 v[18:19], v[70:71], v[18:19]
	global_store_dwordx4 v[148:149], v[52:55], off
	global_store_dwordx4 v[148:149], v[56:59], off offset:16
	global_store_dwordx4 v[148:149], v[60:63], off offset:32
	global_store_dwordx4 v[148:149], v[64:67], off offset:48
	global_store_dwordx4 v[148:149], v[36:39], off offset:64
	global_store_dwordx4 v[148:149], v[40:43], off offset:80
	global_store_dwordx4 v[148:149], v[44:47], off offset:96
	global_store_dwordx4 v[148:149], v[48:51], off offset:112
	global_store_dwordx4 v[148:149], v[20:23], off offset:128
	global_store_dwordx4 v[148:149], v[24:27], off offset:144
	global_store_dwordx4 v[148:149], v[28:31], off offset:160
	global_store_dwordx4 v[148:149], v[32:35], off offset:176
	global_store_dwordx4 v[148:149], v[4:7], off offset:192
	global_store_dwordx4 v[148:149], v[8:11], off offset:208
	global_store_dwordx4 v[148:149], v[12:15], off offset:224
	global_store_dwordx4 v[148:149], v[16:19], off offset:240
	v_mov_b32_e32 v163, 0
	v_mov_b32_e32 v12, v0
	v_mov_b32_e32 v18, v3
	v_readfirstlane_b32 s1, v12
	s_ashr_i32 s2, s1, 6
	v_and_b32_e32 v13, 31, v12
	s_lshl_b32 s3, s2, 5
	v_or_b32_e32 v4, s3, v13
	v_ashrrev_i32_e32 v5, 31, v4
	v_bfe_u32 v14, v12, 5, 1
	v_lshlrev_b64 v[4:5], 8, v[4:5]
	v_lshl_add_u64 v[4:5], s[6:7], 0, v[4:5]
	v_lshlrev_b32_e32 v2, 4, v14
	v_lshl_add_u64 v[4:5], v[4:5], 0, v[2:3]
	global_load_dwordx4 v[100:103], v[4:5], off
	global_load_dwordx4 v[104:107], v[4:5], off offset:32
	global_load_dwordx4 v[108:111], v[4:5], off offset:64
	global_load_dwordx4 v[112:115], v[4:5], off offset:96
	v_ashrrev_i32_e32 v5, 4, v12
	v_lshlrev_b32_e32 v6, 1, v5
	v_lshrrev_b32_e32 v7, 1, v5
	v_and_b32_e32 v4, 0x1fffff3, v5
	v_and_b32_e32 v6, 8, v6
	v_and_b32_e32 v7, 4, v7
	v_or3_b32 v4, v4, v6, v7
	v_and_b32_e32 v6, 15, v12
	v_bitop3_b32 v6, v5, v6, 7 bitop3:0x6c
	v_lshlrev_b32_e32 v6, 3, v6
	v_lshl_or_b32 v4, v4, 7, v6
	v_bfe_u32 v6, v12, 2, 2
	v_and_or_b32 v5, v5, s90, v6
	v_lshrrev_b32_e32 v6, 1, v12
	v_and_b32_e32 v6, 8, v6
	v_or3_b32 v5, v5, v6, v7
	v_lshlrev_b32_e32 v15, 3, v12
	v_lshlrev_b32_e32 v5, 7, v5
	v_and_b32_e32 v6, 0x60, v12
	v_and_b32_e32 v7, 24, v15
	v_or3_b32 v6, v5, v6, v7
	s_lshl_b32 s2, s2, 10
	v_ashrrev_i32_e32 v5, 31, v4
	v_lshlrev_b64 v[4:5], 1, v[4:5]
	s_add_i32 s8, s2, 0
	v_lshl_add_u64 v[8:9], s[80:81], 0, v[4:5]
	v_ashrrev_i32_e32 v7, 31, v6
	s_add_i32 m0, s8, 0x1c000
	v_lshlrev_b64 v[6:7], 1, v[6:7]
	global_load_lds_dwordx4 v[8:9], off
	v_lshl_add_u64 v[8:9], v[8:9], 0, s[84:85]
	s_add_i32 m0, s8, 0x1e000
	v_lshl_add_u64 v[10:11], s[96:97], 0, v[6:7]
	global_load_lds_dwordx4 v[8:9], off
	s_add_i32 m0, s8, 0xc000
	v_lshl_add_u64 v[8:9], v[10:11], 0, s[84:85]
	global_load_lds_dwordx4 v[10:11], off
	s_add_i32 m0, s8, 0xe000
	v_lshl_add_u64 v[10:11], s[88:89], 0, v[6:7]
	global_load_lds_dwordx4 v[8:9], off
	v_lshl_add_u64 v[8:9], s[82:83], 0, v[4:5]
	s_add_i32 m0, s8, 0x18000
	s_and_b32 s1, s1, 0x3fffffc0
	global_load_lds_dwordx4 v[8:9], off
	v_lshl_add_u64 v[8:9], v[8:9], 0, s[84:85]
	s_add_i32 m0, s8, 0x1a000
	v_lshl_add_u64 v[150:151], s[74:75], 0, v[4:5]
	global_load_lds_dwordx4 v[8:9], off
	s_add_i32 m0, s8, 0x8000
	v_lshl_add_u64 v[8:9], v[10:11], 0, s[84:85]
	global_load_lds_dwordx4 v[10:11], off
	s_add_i32 m0, s8, 0xa000
	v_lshlrev_b32_e32 v4, 1, v12
	global_load_lds_dwordx4 v[8:9], off
	s_lshl_b32 s1, s1, 2
	v_and_b32_e32 v4, 32, v4
	v_lshlrev_b32_e32 v5, 4, v12
	s_add_i32 s78, s1, 0
	s_add_i32 s79, s3, s9
	v_lshl_add_u64 v[152:153], s[76:77], 0, v[6:7]
	v_and_b32_e32 v6, 0xc0, v5
	v_and_or_b32 v4, v15, s93, v4
	s_movk_i32 s2, 0x70
	s_addk_i32 s3, 0xff40
	s_add_i32 s78, s78, 0x20400
	v_and_b32_e32 v8, 63, v12
	v_lshlrev_b32_e32 v9, 3, v14
	s_waitcnt vmcnt(0)
	v_and_b32_e32 v7, 0x70, v5
	v_bitop3_b32 v156, v2, v5, s2 bitop3:0x78
	s_movk_i32 s2, 0x60
	v_add3_u32 v160, v6, 0, v4
	v_or_b32_e32 v4, s3, v13
	v_mov_b32_e32 v19, v3
	v_lshlrev_b32_e32 v154, 8, v13
	v_bitop3_b32 v157, v2, v7, 32 bitop3:0x36
	v_bitop3_b32 v158, v2, v7, 64 bitop3:0x36
	v_bitop3_b32 v159, v2, v7, s2 bitop3:0x36
	v_cmp_gt_u32_e64 s[10:11], 32, v8
	v_lshl_add_u32 v155, v13, 2, s78
	v_sub_u32_e32 v161, v4, v9
	v_mov_b32_e32 v4, v3
	v_mov_b32_e32 v5, v3
	v_mov_b32_e32 v6, v3
	v_mov_b32_e32 v7, v3
	v_mov_b32_e32 v8, v3
	v_mov_b32_e32 v9, v3
	v_mov_b32_e32 v10, v3
	v_mov_b32_e32 v11, v3
	v_mov_b32_e32 v12, v3
	v_mov_b32_e32 v13, v3
	v_mov_b32_e32 v14, v3
	v_mov_b32_e32 v15, v3
	v_mov_b32_e32 v16, v3
	v_mov_b32_e32 v17, v3
	v_mov_b64_e32 v[34:35], v[18:19]
	v_mov_b64_e32 v[50:51], v[18:19]
	v_mov_b64_e32 v[66:67], v[18:19]
	s_add_i32 s1, s8, 0x10000
	s_or_b32 s80, s79, 31
	v_mov_b32_e32 v162, 0xf149f2ca
	v_mov_b32_e32 v240, 0xf149f2ca
	v_mov_b64_e32 v[184:185], 0
	v_mov_b64_e32 v[186:187], 0
	v_mov_b64_e32 v[188:189], 0
	v_mov_b64_e32 v[190:191], 0
	v_mov_b64_e32 v[192:193], 0
	v_mov_b64_e32 v[194:195], 0
	v_mov_b64_e32 v[196:197], 0
	v_mov_b64_e32 v[198:199], 0
	s_mov_b32 s2, s9
	v_mov_b64_e32 v[32:33], v[16:17]
	v_mov_b64_e32 v[30:31], v[14:15]
	v_mov_b64_e32 v[28:29], v[12:13]
	v_mov_b64_e32 v[26:27], v[10:11]
	v_mov_b64_e32 v[24:25], v[8:9]
	v_mov_b64_e32 v[22:23], v[6:7]
	v_mov_b64_e32 v[20:21], v[4:5]
	v_mov_b64_e32 v[48:49], v[16:17]
	v_mov_b64_e32 v[46:47], v[14:15]
	v_mov_b64_e32 v[44:45], v[12:13]
	v_mov_b64_e32 v[42:43], v[10:11]
	v_mov_b64_e32 v[40:41], v[8:9]
	v_mov_b64_e32 v[38:39], v[6:7]
	v_mov_b64_e32 v[36:37], v[4:5]
	v_mov_b64_e32 v[64:65], v[16:17]
	v_mov_b64_e32 v[62:63], v[14:15]
	v_mov_b64_e32 v[60:61], v[12:13]
	v_mov_b64_e32 v[58:59], v[10:11]
	v_mov_b64_e32 v[56:57], v[8:9]
	v_mov_b64_e32 v[54:55], v[6:7]
	v_mov_b64_e32 v[52:53], v[4:5]
	s_waitcnt vmcnt(0) lgkmcnt(0)
	s_barrier
	s_branch .LBB0_943

.LBB0_947:
	s_add_i32 s4, s0, 0xc000
	s_and_b32 s4, s4, 0xc000
	s_add_i32 s12, s4, 0
	s_add_i32 s12, s12, 0x10000
	v_add_u32_e32 v76, s12, v154
	v_add_u32_e32 v77, v76, v156
	ds_read_b128 v[68:71], v77 offset:0
	ds_read_b128 v[72:75], v77 offset:0x2000
	v_add_u32_e32 v77, v76, v157
	ds_read_b128 v[116:119], v77 offset:0
	ds_read_b128 v[120:123], v77 offset:0x2000
	v_add_u32_e32 v77, v76, v158
	ds_read_b128 v[124:127], v77 offset:0
	ds_read_b128 v[128:131], v77 offset:0x2000
	v_add_u32_e32 v76, v76, v159
	ds_read_b128 v[132:135], v76 offset:0
	ds_read_b128 v[136:139], v76 offset:0x2000
	s_waitcnt lgkmcnt(4)
	s_add_i32 s3, s2, 0xff
	s_cmp_le_u32 s3, s79
	v_mfma_f32_32x32x16_bf16 v[84:99], v[68:71], v[100:103], v[184:199]
	v_mfma_f32_32x32x16_bf16 v[84:99], v[116:119], v[104:107], v[84:99]
	v_mfma_f32_32x32x16_bf16 v[68:83], v[72:75], v[100:103], v[184:199]
	v_mfma_f32_32x32x16_bf16 v[68:83], v[120:123], v[104:107], v[68:83]
	s_waitcnt lgkmcnt(0)
	v_mfma_f32_32x32x16_bf16 v[84:99], v[124:127], v[108:111], v[84:99]
	v_mfma_f32_32x32x16_bf16 v[84:99], v[132:135], v[112:115], v[84:99]
	v_mfma_f32_32x32x16_bf16 v[68:83], v[128:131], v[108:111], v[68:83]
	v_mfma_f32_32x32x16_bf16 v[68:83], v[136:139], v[112:115], v[68:83]
	v_add_u32_e32 v164, s4, v160
	ds_read_b64_tr_b16 v[144:145], v164 offset:0
	ds_read_b64_tr_b16 v[146:147], v164 offset:0x800
	ds_read_b64_tr_b16 v[140:141], v164 offset:0x1000
	ds_read_b64_tr_b16 v[142:143], v164 offset:0x1800
	ds_read_b64_tr_b16 v[136:137], v164 offset:0x2000
	ds_read_b64_tr_b16 v[138:139], v164 offset:0x2800
	ds_read_b64_tr_b16 v[132:133], v164 offset:0x3000
	ds_read_b64_tr_b16 v[134:135], v164 offset:0x3800
	ds_read_b64_tr_b16 v[128:129], v164 offset:0x200
	ds_read_b64_tr_b16 v[130:131], v164 offset:0xa00
	ds_read_b64_tr_b16 v[124:125], v164 offset:0x1200
	ds_read_b64_tr_b16 v[126:127], v164 offset:0x1a00
	ds_read_b64_tr_b16 v[120:121], v164 offset:0x2200
	ds_read_b64_tr_b16 v[122:123], v164 offset:0x2a00
	ds_read_b64_tr_b16 v[116:117], v164 offset:0x3200
	ds_read_b64_tr_b16 v[118:119], v164 offset:0x3a00
	s_cbranch_scc1 .LBB0_949
	v_cmp_gt_i32_e64 s[70:71], 22, v161
	v_cmp_gt_i32_e64 s[72:73], 23, v161
	v_cmp_gt_i32_e64 s[68:69], 21, v161
	s_and_b64 s[70:71], s[72:73], s[70:71]
	v_cmp_gt_i32_e64 s[66:67], 20, v161
	s_and_b64 s[68:69], s[70:71], s[68:69]
	v_cmp_gt_i32_e64 s[64:65], 19, v161
	s_and_b64 s[66:67], s[68:69], s[66:67]
	v_cmp_gt_i32_e64 s[62:63], 18, v161
	s_and_b64 s[64:65], s[66:67], s[64:65]
	v_cmp_gt_i32_e64 s[60:61], 17, v161
	s_and_b64 s[62:63], s[64:65], s[62:63]
	v_cmp_gt_i32_e64 s[58:59], 16, v161
	s_and_b64 s[60:61], s[62:63], s[60:61]
	v_cmp_gt_i32_e64 s[56:57], 7, v161
	s_and_b64 s[58:59], s[60:61], s[58:59]
	v_cmp_gt_i32_e64 s[54:55], 6, v161
	s_and_b64 s[56:57], s[58:59], s[56:57]
	v_cmp_gt_i32_e64 s[52:53], 5, v161
	s_and_b64 s[54:55], s[56:57], s[54:55]
	v_cmp_gt_i32_e64 s[50:51], 4, v161
	s_and_b64 s[52:53], s[54:55], s[52:53]
	v_cmp_gt_i32_e64 s[48:49], 3, v161
	s_and_b64 s[50:51], s[52:53], s[50:51]
	v_cmp_gt_i32_e64 s[46:47], 2, v161
	s_and_b64 s[48:49], s[50:51], s[48:49]
	v_cmp_gt_i32_e64 s[44:45], 1, v161
	s_and_b64 s[46:47], s[48:49], s[46:47]
	v_cmp_gt_i32_e64 s[42:43], 0, v161
	s_and_b64 s[44:45], s[46:47], s[44:45]
	s_and_b64 s[42:43], s[44:45], s[42:43]
	v_cmp_gt_i32_e64 s[40:41], 54, v161
	v_cndmask_b32_e64 v84, v84, v204, s[42:43]
	v_cmp_gt_i32_e64 s[42:43], 55, v161
	v_cmp_gt_i32_e64 s[38:39], 53, v161
	s_and_b64 s[40:41], s[42:43], s[40:41]
	v_cmp_gt_i32_e64 s[36:37], 52, v161
	s_and_b64 s[38:39], s[40:41], s[38:39]
	v_cmp_gt_i32_e64 s[34:35], 51, v161
	s_and_b64 s[36:37], s[38:39], s[36:37]
	v_cmp_gt_i32_e64 s[30:31], 50, v161
	s_and_b64 s[34:35], s[36:37], s[34:35]
	v_cmp_gt_i32_e64 s[28:29], 49, v161
	s_and_b64 s[30:31], s[34:35], s[30:31]
	v_cmp_gt_i32_e64 s[26:27], 48, v161
	s_and_b64 s[28:29], s[30:31], s[28:29]
	v_cmp_gt_i32_e64 s[24:25], 39, v161
	s_and_b64 s[26:27], s[28:29], s[26:27]
	v_cmp_gt_i32_e64 s[22:23], 38, v161
	s_and_b64 s[24:25], s[26:27], s[24:25]
	v_cmp_gt_i32_e64 s[20:21], 37, v161
	s_and_b64 s[22:23], s[24:25], s[22:23]
	v_cmp_gt_i32_e64 s[18:19], 36, v161
	s_and_b64 s[20:21], s[22:23], s[20:21]
	v_cmp_gt_i32_e64 s[16:17], 35, v161
	s_and_b64 s[18:19], s[20:21], s[18:19]
	v_cmp_gt_i32_e64 s[14:15], 34, v161
	s_and_b64 s[16:17], s[18:19], s[16:17]
	v_cmp_gt_i32_e64 s[12:13], 33, v161
	s_and_b64 s[14:15], s[16:17], s[14:15]
	v_cmp_gt_i32_e32 vcc, 32, v161
	s_and_b64 s[12:13], s[14:15], s[12:13]
	s_and_b64 vcc, s[12:13], vcc
	v_cndmask_b32_e64 v99, v99, v204, s[72:73]
	v_cndmask_b32_e64 v98, v98, v204, s[70:71]
	v_cndmask_b32_e64 v97, v97, v204, s[68:69]
	v_cndmask_b32_e64 v96, v96, v204, s[66:67]
	v_cndmask_b32_e64 v95, v95, v204, s[64:65]
	v_cndmask_b32_e64 v94, v94, v204, s[62:63]
	v_cndmask_b32_e64 v93, v93, v204, s[60:61]
	v_cndmask_b32_e64 v92, v92, v204, s[58:59]
	v_cndmask_b32_e64 v91, v91, v204, s[56:57]
	v_cndmask_b32_e64 v90, v90, v204, s[54:55]
	v_cndmask_b32_e64 v89, v89, v204, s[52:53]
	v_cndmask_b32_e64 v88, v88, v204, s[50:51]
	v_cndmask_b32_e64 v87, v87, v204, s[48:49]
	v_cndmask_b32_e64 v86, v86, v204, s[46:47]
	v_cndmask_b32_e64 v85, v85, v204, s[44:45]
	v_cndmask_b32_e64 v83, v83, v204, s[42:43]
	v_cndmask_b32_e64 v82, v82, v204, s[40:41]
	v_cndmask_b32_e64 v81, v81, v204, s[38:39]
	v_cndmask_b32_e64 v80, v80, v204, s[36:37]
	v_cndmask_b32_e64 v79, v79, v204, s[34:35]
	v_cndmask_b32_e64 v78, v78, v204, s[30:31]
	v_cndmask_b32_e64 v77, v77, v204, s[28:29]
	v_cndmask_b32_e64 v76, v76, v204, s[26:27]
	v_cndmask_b32_e64 v75, v75, v204, s[24:25]
	v_cndmask_b32_e64 v74, v74, v204, s[22:23]
	v_cndmask_b32_e64 v73, v73, v204, s[20:21]
	v_cndmask_b32_e64 v72, v72, v204, s[18:19]
	v_cndmask_b32_e64 v71, v71, v204, s[16:17]
	v_cndmask_b32_e64 v70, v70, v204, s[14:15]
	v_cndmask_b32_e64 v69, v69, v204, s[12:13]
	v_cndmask_b32_e32 v68, v68, v204, vcc
.LBB0_949:
	s_nop 8
	v_max_f32_e32 v165, v84, v85
	v_max3_f32 v165, v165, v86, v87
	v_max3_f32 v165, v165, v88, v89
	v_max3_f32 v165, v165, v90, v91
	v_max3_f32 v165, v165, v92, v93
	v_max3_f32 v165, v165, v94, v95
	v_max3_f32 v165, v165, v96, v97
	v_max3_f32 v165, v165, v98, v99
	v_max3_f32 v165, v165, v68, v69
	v_max3_f32 v165, v165, v70, v71
	v_max3_f32 v165, v165, v72, v73
	v_max3_f32 v165, v165, v74, v75
	v_max3_f32 v165, v165, v76, v77
	v_max3_f32 v165, v165, v78, v79
	v_max3_f32 v165, v165, v80, v81
	v_max3_f32 v165, v165, v82, v83
	v_mov_b32_e32 v166, v165
	s_nop 1
	v_permlane32_swap_b32_e32 v165, v166
	v_max_f32_e32 v166, v165, v166
	v_sub_f32_e32 v165, v166, v240
	v_cmp_ge_f32_e32 vcc, s91, v165
	s_cmp_eq_u64 vcc, exec
	v_mov_b32_e32 v165, 1.0
	s_cbranch_scc0 .LBB0_961
.LBB0_950:
	v_exp_f32_e32 v166, v84
	v_exp_f32_e32 v85, v85
	v_exp_f32_e32 v86, v86
	v_exp_f32_e32 v87, v87
	v_exp_f32_e32 v88, v88
	v_exp_f32_e32 v89, v89
	v_exp_f32_e32 v90, v90
	v_exp_f32_e32 v167, v91
	v_exp_f32_e32 v84, v75
	v_exp_f32_e32 v91, v92
	v_exp_f32_e32 v92, v93
	v_exp_f32_e32 v93, v94
	v_exp_f32_e32 v94, v95
	v_exp_f32_e32 v95, v96
	v_exp_f32_e32 v96, v97
	v_exp_f32_e32 v97, v98
	v_exp_f32_e32 v98, v99
	v_mov_b32_e32 v243, v83
	v_add_f32_e32 v83, 0, v166
	v_add_f32_e32 v83, v85, v83
	v_add_f32_e32 v83, v86, v83
	v_add_f32_e32 v83, v87, v83
	v_add_f32_e32 v83, v88, v83
	v_add_f32_e32 v83, v89, v83
	v_add_f32_e32 v83, v90, v83
	v_add_f32_e32 v83, v167, v83
	v_add_f32_e32 v83, v91, v83
	v_add_f32_e32 v83, v92, v83
	v_add_f32_e32 v83, v93, v83
	v_add_f32_e32 v83, v94, v83
	v_exp_f32_e32 v68, v68
	v_add_f32_e32 v83, v95, v83
	v_exp_f32_e32 v69, v69
	v_add_f32_e32 v83, v96, v83
	v_exp_f32_e32 v70, v70
	v_add_f32_e32 v83, v97, v83
	v_exp_f32_e32 v71, v71
	v_add_f32_e32 v83, v98, v83
	v_exp_f32_e32 v72, v72
	v_add_f32_e32 v83, v68, v83
	v_exp_f32_e32 v73, v73
	v_add_f32_e32 v83, v69, v83
	v_exp_f32_e32 v74, v74
	v_add_f32_e32 v83, v70, v83
	v_add_f32_e32 v83, v71, v83
	v_exp_f32_e32 v75, v76
	v_add_f32_e32 v83, v72, v83
	v_exp_f32_e32 v76, v77
	v_add_f32_e32 v83, v73, v83
	v_exp_f32_e32 v77, v78
	v_add_f32_e32 v83, v74, v83
	v_exp_f32_e32 v78, v79
	v_add_f32_e32 v83, v84, v83
	v_exp_f32_e32 v79, v80
	v_add_f32_e32 v83, v75, v83
	v_exp_f32_e32 v80, v81
	v_add_f32_e32 v83, v76, v83
	v_exp_f32_e32 v81, v82
	v_add_f32_e32 v83, v77, v83
	v_exp_f32_e32 v82, v243
	v_add_f32_e32 v83, v78, v83
	v_add_f32_e32 v83, v79, v83
	v_add_f32_e32 v83, v80, v83
	v_add_f32_e32 v83, v81, v83
	v_add_f32_e32 v83, v82, v83
	v_mov_b32_e32 v99, v83
	s_nop 1
	v_permlane32_swap_b32_e32 v83, v99
	v_cmp_gt_f32_e32 vcc, 1.0, v165
	s_cbranch_vccz .LBB0_954
	s_and_saveexec_b64 s[12:13], s[10:11]
	ds_write_b32 v155, v165 offset:128
	s_or_b64 exec, exec, s[12:13]
	s_waitcnt lgkmcnt(0)
	v_add_u32_e32 v180, s78, v2
	ds_read_b128 v[168:171], v180 offset:224
	ds_read_b128 v[172:175], v180 offset:192
	ds_read_b128 v[176:179], v180 offset:160
	ds_read_b128 v[180:183], v180 offset:128
	s_waitcnt lgkmcnt(0)
	s_waitcnt lgkmcnt(0)
	v_pk_mul_f32 v[64:65], v[168:169], v[64:65]
	v_pk_mul_f32 v[60:61], v[172:173], v[60:61]
	v_pk_mul_f32 v[56:57], v[176:177], v[56:57]
	v_pk_mul_f32 v[66:67], v[170:171], v[66:67]
	v_pk_mul_f32 v[62:63], v[174:175], v[62:63]
	v_pk_mul_f32 v[58:59], v[178:179], v[58:59]
	v_pk_mul_f32 v[54:55], v[182:183], v[54:55]
	v_pk_mul_f32 v[52:53], v[180:181], v[52:53]
	v_pk_mul_f32 v[48:49], v[168:169], v[48:49]
	v_pk_mul_f32 v[44:45], v[172:173], v[44:45]
	v_pk_mul_f32 v[40:41], v[176:177], v[40:41]
	v_pk_mul_f32 v[50:51], v[170:171], v[50:51]
	v_pk_mul_f32 v[46:47], v[174:175], v[46:47]
	v_pk_mul_f32 v[42:43], v[178:179], v[42:43]
	v_pk_mul_f32 v[38:39], v[182:183], v[38:39]
	v_pk_mul_f32 v[36:37], v[180:181], v[36:37]
	v_pk_mul_f32 v[32:33], v[168:169], v[32:33]
	v_pk_mul_f32 v[28:29], v[172:173], v[28:29]
	v_pk_mul_f32 v[24:25], v[176:177], v[24:25]
	v_pk_mul_f32 v[34:35], v[170:171], v[34:35]
	v_pk_mul_f32 v[30:31], v[174:175], v[30:31]
	v_pk_mul_f32 v[26:27], v[178:179], v[26:27]
	v_pk_mul_f32 v[22:23], v[182:183], v[22:23]
	v_pk_mul_f32 v[20:21], v[180:181], v[20:21]
	v_pk_mul_f32 v[16:17], v[168:169], v[16:17]
	v_pk_mul_f32 v[12:13], v[172:173], v[12:13]
	v_pk_mul_f32 v[8:9], v[176:177], v[8:9]
	v_pk_mul_f32 v[18:19], v[170:171], v[18:19]
	v_pk_mul_f32 v[14:15], v[174:175], v[14:15]
	v_pk_mul_f32 v[10:11], v[178:179], v[10:11]
	v_pk_mul_f32 v[6:7], v[182:183], v[6:7]
	v_pk_mul_f32 v[4:5], v[180:181], v[4:5]

.LBB0_955:
	s_add_i32 s4, s0, 0x8000
	s_and_b32 s4, s4, 0xc000
	s_add_i32 s12, s4, 0
	s_add_i32 s12, s12, 0x10000
	v_add_u32_e32 v76, s12, v154
	v_add_u32_e32 v77, v76, v156
	ds_read_b128 v[68:71], v77 offset:0
	ds_read_b128 v[72:75], v77 offset:0x2000
	v_add_u32_e32 v77, v76, v157
	ds_read_b128 v[116:119], v77 offset:0
	ds_read_b128 v[120:123], v77 offset:0x2000
	v_add_u32_e32 v77, v76, v158
	ds_read_b128 v[124:127], v77 offset:0
	ds_read_b128 v[128:131], v77 offset:0x2000
	v_add_u32_e32 v76, v76, v159
	ds_read_b128 v[132:135], v76 offset:0
	ds_read_b128 v[136:139], v76 offset:0x2000
	s_waitcnt lgkmcnt(4)
	s_add_i32 s3, s2, 0xbf
	s_cmp_le_i32 s3, s79
	v_mfma_f32_32x32x16_bf16 v[84:99], v[68:71], v[100:103], v[184:199]
	v_mfma_f32_32x32x16_bf16 v[84:99], v[116:119], v[104:107], v[84:99]
	v_mfma_f32_32x32x16_bf16 v[68:83], v[72:75], v[100:103], v[184:199]
	v_mfma_f32_32x32x16_bf16 v[68:83], v[120:123], v[104:107], v[68:83]
	s_waitcnt lgkmcnt(0)
	v_mfma_f32_32x32x16_bf16 v[84:99], v[124:127], v[108:111], v[84:99]
	v_mfma_f32_32x32x16_bf16 v[84:99], v[132:135], v[112:115], v[84:99]
	v_mfma_f32_32x32x16_bf16 v[68:83], v[128:131], v[108:111], v[68:83]
	v_mfma_f32_32x32x16_bf16 v[68:83], v[136:139], v[112:115], v[68:83]
	v_add_u32_e32 v164, s4, v160
	ds_read_b64_tr_b16 v[144:145], v164 offset:0
	ds_read_b64_tr_b16 v[146:147], v164 offset:0x800
	ds_read_b64_tr_b16 v[140:141], v164 offset:0x1000
	ds_read_b64_tr_b16 v[142:143], v164 offset:0x1800
	ds_read_b64_tr_b16 v[136:137], v164 offset:0x2000
	ds_read_b64_tr_b16 v[138:139], v164 offset:0x2800
	ds_read_b64_tr_b16 v[132:133], v164 offset:0x3000
	ds_read_b64_tr_b16 v[134:135], v164 offset:0x3800
	ds_read_b64_tr_b16 v[128:129], v164 offset:0x200
	ds_read_b64_tr_b16 v[130:131], v164 offset:0xa00
	ds_read_b64_tr_b16 v[124:125], v164 offset:0x1200
	ds_read_b64_tr_b16 v[126:127], v164 offset:0x1a00
	ds_read_b64_tr_b16 v[120:121], v164 offset:0x2200
	ds_read_b64_tr_b16 v[122:123], v164 offset:0x2a00
	ds_read_b64_tr_b16 v[116:117], v164 offset:0x3200
	ds_read_b64_tr_b16 v[118:119], v164 offset:0x3a00
	s_cbranch_scc1 .LBB0_957
	v_add_u32_e32 v165, 64, v161
	v_cmp_gt_i32_e64 s[70:71], 22, v165
	v_cmp_gt_i32_e64 s[72:73], 23, v165
	v_cmp_gt_i32_e64 s[68:69], 21, v165
	s_and_b64 s[70:71], s[72:73], s[70:71]
	v_cmp_gt_i32_e64 s[66:67], 20, v165
	s_and_b64 s[68:69], s[70:71], s[68:69]
	v_cmp_gt_i32_e64 s[64:65], 19, v165
	s_and_b64 s[66:67], s[68:69], s[66:67]
	v_cmp_gt_i32_e64 s[62:63], 18, v165
	s_and_b64 s[64:65], s[66:67], s[64:65]
	v_cmp_gt_i32_e64 s[60:61], 17, v165
	s_and_b64 s[62:63], s[64:65], s[62:63]
	v_cmp_gt_i32_e64 s[58:59], 16, v165
	s_and_b64 s[60:61], s[62:63], s[60:61]
	v_cmp_gt_i32_e64 s[56:57], 7, v165
	s_and_b64 s[58:59], s[60:61], s[58:59]
	v_cmp_gt_i32_e64 s[54:55], 6, v165
	s_and_b64 s[56:57], s[58:59], s[56:57]
	v_cmp_gt_i32_e64 s[52:53], 5, v165
	s_and_b64 s[54:55], s[56:57], s[54:55]
	v_cmp_gt_i32_e64 s[50:51], 4, v165
	s_and_b64 s[52:53], s[54:55], s[52:53]
	v_cmp_gt_i32_e64 s[48:49], 3, v165
	s_and_b64 s[50:51], s[52:53], s[50:51]
	v_cmp_gt_i32_e64 s[46:47], 2, v165
	s_and_b64 s[48:49], s[50:51], s[48:49]
	v_cmp_gt_i32_e64 s[44:45], 1, v165
	s_and_b64 s[46:47], s[48:49], s[46:47]
	v_cmp_gt_i32_e64 s[42:43], 0, v165
	s_and_b64 s[44:45], s[46:47], s[44:45]
	s_and_b64 s[42:43], s[44:45], s[42:43]
	v_cmp_gt_i32_e64 s[40:41], 54, v165
	v_cndmask_b32_e64 v84, v84, v204, s[42:43]
	v_cmp_gt_i32_e64 s[42:43], 55, v165
	v_cmp_gt_i32_e64 s[38:39], 53, v165
	s_and_b64 s[40:41], s[42:43], s[40:41]
	v_cmp_gt_i32_e64 s[36:37], 52, v165
	s_and_b64 s[38:39], s[40:41], s[38:39]
	v_cmp_gt_i32_e64 s[34:35], 51, v165
	s_and_b64 s[36:37], s[38:39], s[36:37]
	v_cmp_gt_i32_e64 s[30:31], 50, v165
	s_and_b64 s[34:35], s[36:37], s[34:35]
	v_cmp_gt_i32_e64 s[28:29], 49, v165
	s_and_b64 s[30:31], s[34:35], s[30:31]
	v_cmp_gt_i32_e64 s[26:27], 48, v165
	s_and_b64 s[28:29], s[30:31], s[28:29]
	v_cmp_gt_i32_e64 s[24:25], 39, v165
	s_and_b64 s[26:27], s[28:29], s[26:27]
	v_cmp_gt_i32_e64 s[22:23], 38, v165
	s_and_b64 s[24:25], s[26:27], s[24:25]
	v_cmp_gt_i32_e64 s[20:21], 37, v165
	s_and_b64 s[22:23], s[24:25], s[22:23]
	v_cmp_gt_i32_e64 s[18:19], 36, v165
	s_and_b64 s[20:21], s[22:23], s[20:21]
	v_cmp_gt_i32_e64 s[16:17], 35, v165
	s_and_b64 s[18:19], s[20:21], s[18:19]
	v_cmp_gt_i32_e64 s[14:15], 34, v165
	s_and_b64 s[16:17], s[18:19], s[16:17]
	v_cmp_gt_i32_e64 s[12:13], 33, v165
	s_and_b64 s[14:15], s[16:17], s[14:15]
	v_cmp_gt_i32_e32 vcc, 32, v165
	s_and_b64 s[12:13], s[14:15], s[12:13]
	s_and_b64 vcc, s[12:13], vcc
	v_cndmask_b32_e64 v99, v99, v204, s[72:73]
	v_cndmask_b32_e64 v98, v98, v204, s[70:71]
	v_cndmask_b32_e64 v97, v97, v204, s[68:69]
	v_cndmask_b32_e64 v96, v96, v204, s[66:67]
	v_cndmask_b32_e64 v95, v95, v204, s[64:65]
	v_cndmask_b32_e64 v94, v94, v204, s[62:63]
	v_cndmask_b32_e64 v93, v93, v204, s[60:61]
	v_cndmask_b32_e64 v92, v92, v204, s[58:59]
	v_cndmask_b32_e64 v91, v91, v204, s[56:57]
	v_cndmask_b32_e64 v90, v90, v204, s[54:55]
	v_cndmask_b32_e64 v89, v89, v204, s[52:53]
	v_cndmask_b32_e64 v88, v88, v204, s[50:51]
	v_cndmask_b32_e64 v87, v87, v204, s[48:49]
	v_cndmask_b32_e64 v86, v86, v204, s[46:47]
	v_cndmask_b32_e64 v85, v85, v204, s[44:45]
	v_cndmask_b32_e64 v83, v83, v204, s[42:43]
	v_cndmask_b32_e64 v82, v82, v204, s[40:41]
	v_cndmask_b32_e64 v81, v81, v204, s[38:39]
	v_cndmask_b32_e64 v80, v80, v204, s[36:37]
	v_cndmask_b32_e64 v79, v79, v204, s[34:35]
	v_cndmask_b32_e64 v78, v78, v204, s[30:31]
	v_cndmask_b32_e64 v77, v77, v204, s[28:29]
	v_cndmask_b32_e64 v76, v76, v204, s[26:27]
	v_cndmask_b32_e64 v75, v75, v204, s[24:25]
	v_cndmask_b32_e64 v74, v74, v204, s[22:23]
	v_cndmask_b32_e64 v73, v73, v204, s[20:21]
	v_cndmask_b32_e64 v72, v72, v204, s[18:19]
	v_cndmask_b32_e64 v71, v71, v204, s[16:17]
	v_cndmask_b32_e64 v70, v70, v204, s[14:15]
	v_cndmask_b32_e64 v69, v69, v204, s[12:13]
	v_cndmask_b32_e32 v68, v68, v204, vcc

.LBB0_958:
	v_exp_f32_e32 v166, v84
	v_exp_f32_e32 v85, v85
	v_exp_f32_e32 v86, v86
	v_exp_f32_e32 v87, v87
	v_exp_f32_e32 v88, v88
	v_exp_f32_e32 v89, v89
	v_exp_f32_e32 v90, v90
	v_exp_f32_e32 v167, v91
	v_exp_f32_e32 v84, v75
	v_exp_f32_e32 v91, v92
	v_exp_f32_e32 v92, v93
	v_exp_f32_e32 v93, v94
	v_exp_f32_e32 v94, v95
	v_exp_f32_e32 v95, v96
	v_exp_f32_e32 v96, v97
	v_exp_f32_e32 v97, v98
	v_exp_f32_e32 v98, v99
	v_mov_b32_e32 v243, v83
	v_add_f32_e32 v83, 0, v166
	v_add_f32_e32 v83, v85, v83
	v_add_f32_e32 v83, v86, v83
	v_add_f32_e32 v83, v87, v83
	v_add_f32_e32 v83, v88, v83
	v_add_f32_e32 v83, v89, v83
	v_add_f32_e32 v83, v90, v83
	v_add_f32_e32 v83, v167, v83
	v_add_f32_e32 v83, v91, v83
	v_add_f32_e32 v83, v92, v83
	v_add_f32_e32 v83, v93, v83
	v_add_f32_e32 v83, v94, v83
	v_exp_f32_e32 v68, v68
	v_add_f32_e32 v83, v95, v83
	v_exp_f32_e32 v69, v69
	v_add_f32_e32 v83, v96, v83
	v_exp_f32_e32 v70, v70
	v_add_f32_e32 v83, v97, v83
	v_exp_f32_e32 v71, v71
	v_add_f32_e32 v83, v98, v83
	v_exp_f32_e32 v72, v72
	v_add_f32_e32 v83, v68, v83
	v_exp_f32_e32 v73, v73
	v_add_f32_e32 v83, v69, v83
	v_exp_f32_e32 v74, v74
	v_add_f32_e32 v83, v70, v83
	v_add_f32_e32 v83, v71, v83
	v_exp_f32_e32 v75, v76
	v_add_f32_e32 v83, v72, v83
	v_exp_f32_e32 v76, v77
	v_add_f32_e32 v83, v73, v83
	v_exp_f32_e32 v77, v78
	v_add_f32_e32 v83, v74, v83
	v_exp_f32_e32 v78, v79
	v_add_f32_e32 v83, v84, v83
	v_exp_f32_e32 v79, v80
	v_add_f32_e32 v83, v75, v83
	v_exp_f32_e32 v80, v81
	v_add_f32_e32 v83, v76, v83
	v_exp_f32_e32 v81, v82
	v_add_f32_e32 v83, v77, v83
	v_exp_f32_e32 v82, v243
	v_add_f32_e32 v83, v78, v83
	v_add_f32_e32 v83, v79, v83
	v_add_f32_e32 v83, v80, v83
	v_add_f32_e32 v83, v81, v83
	v_add_f32_e32 v83, v82, v83
	v_mov_b32_e32 v99, v83
	s_nop 1
	v_permlane32_swap_b32_e32 v83, v99
	v_cmp_gt_f32_e32 vcc, 1.0, v165
	s_cbranch_vccz .LBB0_941
	s_and_saveexec_b64 s[12:13], s[10:11]
	s_cbranch_execz .LBB0_940
	ds_write_b32 v155, v165 offset:128
	s_branch .LBB0_940
.LBB0_961:
	v_sub_f32_e32 v241, v166, v184
	v_max_f32_e32 v241, v162, v241
	v_sub_f32_e32 v165, v162, v241
	v_exp_f32_e32 v165, v165
	v_add_f32_e32 v242, v241, v184
	v_mov_b32_e32 v162, v241
	v_sub_f32_e32 v84, v84, v242
	v_sub_f32_e32 v85, v85, v242
	v_sub_f32_e32 v86, v86, v242
	v_sub_f32_e32 v87, v87, v242
	v_sub_f32_e32 v88, v88, v242
	v_sub_f32_e32 v89, v89, v242
	v_sub_f32_e32 v90, v90, v242
	v_sub_f32_e32 v91, v91, v242
	v_sub_f32_e32 v92, v92, v242
	v_sub_f32_e32 v93, v93, v242
	v_sub_f32_e32 v94, v94, v242
	v_sub_f32_e32 v95, v95, v242
	v_sub_f32_e32 v96, v96, v242
	v_sub_f32_e32 v97, v97, v242
	v_sub_f32_e32 v98, v98, v242
	v_sub_f32_e32 v99, v99, v242
	v_sub_f32_e32 v68, v68, v242
	v_sub_f32_e32 v69, v69, v242
	v_sub_f32_e32 v70, v70, v242
	v_sub_f32_e32 v71, v71, v242
	v_sub_f32_e32 v72, v72, v242
	v_sub_f32_e32 v73, v73, v242
	v_sub_f32_e32 v74, v74, v242
	v_sub_f32_e32 v75, v75, v242
	v_sub_f32_e32 v76, v76, v242
	v_sub_f32_e32 v77, v77, v242
	v_sub_f32_e32 v78, v78, v242
	v_sub_f32_e32 v79, v79, v242
	v_sub_f32_e32 v80, v80, v242
	v_sub_f32_e32 v81, v81, v242
	v_sub_f32_e32 v82, v82, v242
	v_sub_f32_e32 v83, v83, v242
	v_cmp_lt_f32_e32 vcc, 0xf0000000, v241
	v_sub_f32_e32 v242, 0, v241
	v_cndmask_b32_e32 v242, 0, v242, vcc
	v_add_f32_e32 v240, v241, v242
	v_mov_b32_e32 v184, v242
	v_mov_b32_e32 v185, v242
	v_mov_b32_e32 v186, v242
	v_mov_b32_e32 v187, v242
	v_mov_b32_e32 v188, v242
	v_mov_b32_e32 v189, v242
	v_mov_b32_e32 v190, v242
	v_mov_b32_e32 v191, v242
	v_mov_b32_e32 v192, v242
	v_mov_b32_e32 v193, v242
	v_mov_b32_e32 v194, v242
	v_mov_b32_e32 v195, v242
	v_mov_b32_e32 v196, v242
	v_mov_b32_e32 v197, v242
	v_mov_b32_e32 v198, v242
	v_mov_b32_e32 v199, v242
	s_branch .LBB0_950
